# hid job second layer: trailing 12 LDS operand reads issued four at a time into the four operand quads (was one at a time with a full wait each)
# baseline (speedup 1.0000x reference)
; __device__ __forceinline__ void p0_job(const Params& p, char* smem, int job) {
;     ...
;       float a = b1;
;       for (int i = 0; i < 33; ++i) a += zf[tg * 36 + i] * w1[i * 64 + j];
;       h1s[tg * 64 + j] = sinf(fr * a);
;       __syncthreads();
;       float a2 = b2;
;       for (int i = 0; i < 64; ++i) a2 += h1s[tg * 64 + i] * w2[i * 64 + j];
.LBB0_56:
	s_andn2_saveexec_b64 s[0:1], s[26:27]
	v_mul_f32_e64 v2, |v0|, s56
	v_rndne_f32_e32 v4, v2
	v_cvt_i32_f32_e32 v2, v4
	v_fma_f32 v3, v4, s57, |v0|
	v_fmac_f32_e32 v3, 0xb3a22168, v4
	v_fmac_f32_e32 v3, 0xa7c234c4, v4
	s_or_b64 exec, exec, s[0:1]
	v_mul_f32_e32 v4, v3, v3
	v_fmamk_f32 v147, v4, 0xb94c1982, v150
	v_fmaak_f32 v147, v4, v147, 0xbe2aaa9d
	v_mul_f32_e32 v147, v4, v147
	v_fmac_f32_e32 v3, v3, v147
	v_fmamk_f32 v147, v4, 0x37d75334, v151
	v_fmaak_f32 v147, v4, v147, 0x3d2aabf7
	v_fmaak_f32 v147, v4, v147, 0xbf000004
	v_fma_f32 v4, v4, v147, 1.0
	v_and_b32_e32 v147, 1, v2
	v_lshlrev_b32_e32 v2, 30, v2
	v_cmp_eq_u32_e32 vcc, 0, v147
	v_and_b32_e32 v2, 0x80000000, v2
	v_xor_b32_e32 v1, v1, v0
	v_cndmask_b32_e32 v3, v4, v3, vcc
	v_xor_b32_e32 v1, v1, v2
	v_xor_b32_e32 v1, v1, v3
	v_cmp_class_f32_e64 vcc, v0, s59
	s_nop 1
	v_cndmask_b32_e32 v0, v158, v1, vcc
	ds_write_b32 v167, v0 offset:576
	s_waitcnt lgkmcnt(0)
	s_barrier
	ds_read_b128 v[0:3], v168 offset:576
	ds_read_b128 v[174:177], v168 offset:592
	ds_read_b128 v[178:181], v168 offset:608
	ds_read_b128 v[182:185], v168 offset:624
	global_load_dword v186, v[46:47], off
	global_load_dword v187, v[48:49], off
	global_load_dword v188, v[46:47], off offset:256
	global_load_dword v189, v[46:47], off offset:512
	global_load_dword v190, v[46:47], off offset:768
	global_load_dword v191, v[46:47], off offset:1024
	global_load_dword v192, v[46:47], off offset:1280
	global_load_dword v193, v[46:47], off offset:1536
	global_load_dword v194, v[46:47], off offset:1792
	global_load_dword v195, v[46:47], off offset:2048
	global_load_dword v196, v[46:47], off offset:2304
	global_load_dword v197, v[46:47], off offset:2560
	global_load_dword v198, v[46:47], off offset:2816
	global_load_dword v199, v[46:47], off offset:3072
	global_load_dword v200, v[46:47], off offset:3328
	global_load_dword v201, v[46:47], off offset:3584
	global_load_dword v202, v[46:47], off offset:3840
	global_load_dword v204, v[50:51], off
	global_load_dword v205, v[56:57], off
	global_load_dword v206, v[52:53], off
	global_load_dword v207, v[54:55], off
	global_load_dword v208, v[58:59], off
	global_load_dword v209, v[64:65], off
	global_load_dword v210, v[60:61], off
	global_load_dword v211, v[62:63], off
	global_load_dword v212, v[66:67], off
	global_load_dword v213, v[72:73], off
	global_load_dword v214, v[68:69], off
	global_load_dword v215, v[70:71], off
	global_load_dword v216, v[74:75], off
	global_load_dword v217, v[80:81], off
	global_load_dword v218, v[76:77], off
	global_load_dword v219, v[78:79], off
	global_load_dword v220, v[84:85], off
	global_load_dword v221, v[90:91], off
	global_load_dword v222, v[86:87], off
	global_load_dword v223, v[88:89], off
	global_load_dword v224, v[92:93], off
	global_load_dword v225, v[98:99], off
	global_load_dword v226, v[94:95], off
	global_load_dword v227, v[96:97], off
	global_load_dword v203, v[100:101], off
	global_load_dword v228, v[106:107], off
	global_load_dword v229, v[102:103], off
	global_load_dword v230, v[104:105], off
	global_load_dword v231, v[108:109], off
	global_load_dword v232, v[114:115], off
	global_load_dword v233, v[110:111], off
	global_load_dword v234, v[112:113], off
	global_load_dword v235, v[116:117], off
	global_load_dword v240, v[122:123], off
	global_load_dword v241, v[118:119], off
	global_load_dword v242, v[120:121], off
	global_load_dword v243, v[124:125], off
	global_load_dword v244, v[126:127], off
	global_load_dword v245, v[128:129], off
	global_load_dword v246, v[130:131], off
	global_load_dword v247, v[132:133], off
	global_load_dword v248, v[134:135], off
	global_load_dword v249, v[136:137], off
	global_load_dword v250, v[138:139], off
	global_load_dword v251, v[140:141], off
	global_load_dword v252, v[142:143], off
	global_load_dword v253, v[144:145], off
	s_waitcnt vmcnt(0)
	s_waitcnt lgkmcnt(3)
	v_fma_f32 v4, v0, v186, v163
	v_fmac_f32_e32 v4, v1, v188
	v_fmac_f32_e32 v4, v2, v189
	v_fmac_f32_e32 v4, v3, v190
	s_waitcnt lgkmcnt(2)
	v_fmac_f32_e32 v4, v174, v191
	v_fmac_f32_e32 v4, v175, v192
	v_fmac_f32_e32 v4, v176, v193
	v_fmac_f32_e32 v4, v177, v194
	s_waitcnt lgkmcnt(1)
	v_fmac_f32_e32 v4, v178, v195
	v_fmac_f32_e32 v4, v179, v196
	v_fmac_f32_e32 v4, v180, v197
	v_fmac_f32_e32 v4, v181, v198
	s_waitcnt lgkmcnt(0)
	v_fmac_f32_e32 v4, v182, v199
	v_fmac_f32_e32 v4, v183, v200
	v_fmac_f32_e32 v4, v184, v201
	v_fmac_f32_e32 v4, v185, v202
	ds_read_b128 v[0:3], v168 offset:640
	ds_read_b128 v[174:177], v168 offset:656
	ds_read_b128 v[178:181], v168 offset:672
	ds_read_b128 v[182:185], v168 offset:688
	s_waitcnt lgkmcnt(3)
	v_fmac_f32_e32 v4, v0, v187
	v_fmac_f32_e32 v4, v1, v204
	v_fmac_f32_e32 v4, v2, v206
	v_fmac_f32_e32 v4, v3, v207
	s_waitcnt lgkmcnt(2)
	v_fmac_f32_e32 v4, v174, v205
	v_fmac_f32_e32 v4, v175, v208
	v_fmac_f32_e32 v4, v176, v210
	v_fmac_f32_e32 v4, v177, v211
	s_waitcnt lgkmcnt(1)
	v_fmac_f32_e32 v4, v178, v209
	v_fmac_f32_e32 v4, v179, v212
	v_fmac_f32_e32 v4, v180, v214
	v_fmac_f32_e32 v4, v181, v215
	s_waitcnt lgkmcnt(0)
; __device__ __forceinline__ void p0_job(const Params& p, char* smem, int job) {
;     ...
;       float a2 = b2;
;       for (int i = 0; i < 64; ++i) a2 += h1s[tg * 64 + i] * w2[i * 64 + j];
;       ((float*)(ws + OFF_HYH))[((size_t)l * 8448 + (Lsel ? 8192 : 0) + t) * 64 + j] = sinf(fr * a2);
	v_fmac_f32_e32 v4, v182, v213
	v_fmac_f32_e32 v4, v183, v216
	v_fmac_f32_e32 v4, v184, v218
	v_fmac_f32_e32 v4, v185, v219
	ds_read_b128 v[0:3], v168 offset:704
	ds_read_b128 v[174:177], v168 offset:720
	ds_read_b128 v[178:181], v168 offset:736
	ds_read_b128 v[182:185], v168 offset:752
	s_waitcnt lgkmcnt(3)
	v_fmac_f32_e32 v4, v0, v217
	v_fmac_f32_e32 v4, v1, v220
	v_fmac_f32_e32 v4, v2, v222
	v_fmac_f32_e32 v4, v3, v223
	s_waitcnt lgkmcnt(2)
	v_fmac_f32_e32 v4, v174, v221
	v_fmac_f32_e32 v4, v175, v224
	v_fmac_f32_e32 v4, v176, v226
	v_fmac_f32_e32 v4, v177, v227
	s_waitcnt lgkmcnt(1)
	v_fmac_f32_e32 v4, v178, v225
	v_fmac_f32_e32 v4, v179, v203
	v_fmac_f32_e32 v4, v180, v229
	v_fmac_f32_e32 v4, v181, v230
	s_waitcnt lgkmcnt(0)
	v_fmac_f32_e32 v4, v182, v228
	v_fmac_f32_e32 v4, v183, v231
	v_fmac_f32_e32 v4, v184, v233
	v_fmac_f32_e32 v4, v185, v234
	ds_read_b128 v[0:3], v168 offset:768
	ds_read_b128 v[174:177], v168 offset:784
	ds_read_b128 v[178:181], v168 offset:800
	ds_read_b128 v[182:185], v168 offset:816
	s_waitcnt lgkmcnt(3)
	v_fmac_f32_e32 v4, v0, v232
	v_fmac_f32_e32 v4, v1, v235
	v_fmac_f32_e32 v4, v2, v241
	v_fmac_f32_e32 v4, v3, v242
	s_waitcnt lgkmcnt(2)
	v_fmac_f32_e32 v4, v174, v240
	v_fmac_f32_e32 v4, v175, v243
	v_pk_mul_f32 v[0:1], v[176:177], v[244:245]
	s_nop 0
	v_add_f32_e32 v0, v4, v0
	v_add_f32_e32 v4, v0, v1
	s_waitcnt lgkmcnt(1)
	v_pk_mul_f32 v[0:1], v[178:179], v[246:247]
	s_nop 0
	v_add_f32_e32 v0, v4, v0
	v_add_f32_e32 v4, v0, v1
	v_pk_mul_f32 v[0:1], v[180:181], v[248:249]
	s_nop 0
	v_add_f32_e32 v0, v4, v0
	v_add_f32_e32 v4, v0, v1
	s_waitcnt lgkmcnt(0)
	v_pk_mul_f32 v[0:1], v[182:183], v[250:251]
	s_nop 0
	v_add_f32_e32 v0, v4, v0
	v_add_f32_e32 v4, v0, v1
	v_pk_mul_f32 v[0:1], v[184:185], v[252:253]
	s_nop 0
	v_add_f32_e32 v0, v4, v0
	v_add_f32_e32 v0, v0, v1
	v_mul_f32_e32 v0, v164, v0
	v_and_b32_e32 v1, 0x7fffffff, v0
	v_cmp_nlt_f32_e64 s[0:1], |v0|, s47
	s_and_saveexec_b64 s[10:11], s[0:1]
	s_xor_b64 s[26:27], exec, s[10:11]
	s_cbranch_execz .LBB0_60
	v_lshrrev_b32_e32 v2, 23, v1
	v_add_u32_e32 v2, 0xffffff88, v2
	v_cmp_lt_u32_e32 vcc, 63, v2
	s_nop 1
	v_cndmask_b32_e32 v3, 0, v156, vcc
	v_add_u32_e32 v2, v3, v2
	v_cmp_lt_u32_e64 s[0:1], 31, v2
	s_nop 1
	v_cndmask_b32_e64 v3, 0, v157, s[0:1]
	v_add_u32_e32 v2, v3, v2
	v_cmp_lt_u32_e64 s[12:13], 31, v2
	s_nop 1
	v_cndmask_b32_e64 v3, 0, v157, s[12:13]
	v_add_u32_e32 v147, v3, v2
	v_and_b32_e32 v2, 0x7fffff, v1
	v_or_b32_e32 v173, 0x800000, v2
	v_mad_u64_u32 v[2:3], s[10:11], v173, s48, 0
	v_mov_b32_e32 v4, v3
	v_mad_u64_u32 v[170:171], s[10:11], v173, s49, v[4:5]
	v_mov_b32_e32 v4, v171
	v_mad_u64_u32 v[174:175], s[10:11], v173, s50, v[4:5]
	v_mov_b32_e32 v4, v175
	v_mad_u64_u32 v[176:177], s[10:11], v173, s51, v[4:5]
	v_mov_b32_e32 v4, v177
	v_mad_u64_u32 v[178:179], s[10:11], v173, s52, v[4:5]
	v_mov_b32_e32 v4, v179
	v_mad_u64_u32 v[180:181], s[10:11], v173, s53, v[4:5]
	v_mov_b32_e32 v4, v181
	v_mad_u64_u32 v[182:183], s[10:11], v173, s54, v[4:5]
	v_cndmask_b32_e32 v3, v180, v176, vcc
	v_cndmask_b32_e32 v4, v182, v178, vcc
	v_cndmask_b32_e32 v173, v183, v180, vcc
	v_cndmask_b32_e64 v171, v4, v3, s[0:1]
	v_cndmask_b32_e64 v4, v173, v4, s[0:1]
	v_cndmask_b32_e32 v173, v178, v174, vcc
	v_cndmask_b32_e64 v3, v3, v173, s[0:1]
	v_sub_u32_e32 v175, 32, v147
	v_cmp_eq_u32_e64 s[14:15], 0, v147
	v_cndmask_b32_e32 v147, v176, v170, vcc
	v_cndmask_b32_e64 v4, v4, v171, s[12:13]
	v_cndmask_b32_e64 v171, v171, v3, s[12:13]
	v_cndmask_b32_e64 v170, v173, v147, s[0:1]
	v_alignbit_b32 v177, v4, v171, v175
	v_cndmask_b32_e64 v3, v3, v170, s[12:13]
	v_cndmask_b32_e64 v4, v177, v4, s[14:15]
	v_alignbit_b32 v173, v171, v3, v175
	v_cndmask_b32_e32 v2, v174, v2, vcc
	v_cndmask_b32_e64 v171, v173, v171, s[14:15]
	v_bfe_u32 v177, v4, 29, 1
	v_cndmask_b32_e64 v2, v147, v2, s[0:1]
	v_alignbit_b32 v173, v4, v171, 30
	v_sub_u32_e32 v178, 0, v177
	v_cndmask_b32_e64 v2, v170, v2, s[12:13]
	v_xor_b32_e32 v173, v173, v178
	v_alignbit_b32 v147, v3, v2, v175
	v_cndmask_b32_e64 v3, v147, v3, s[14:15]
	v_ffbh_u32_e32 v170, v173
	v_alignbit_b32 v147, v171, v3, 30
	v_min_u32_e32 v170, 32, v170
	v_alignbit_b32 v2, v3, v2, 30
	v_xor_b32_e32 v147, v147, v178
	v_sub_u32_e32 v171, 31, v170
	v_xor_b32_e32 v2, v2, v178
	v_alignbit_b32 v173, v173, v147, v171
	v_alignbit_b32 v2, v147, v2, v171
	v_alignbit_b32 v3, v173, v2, 9
	v_ffbh_u32_e32 v147, v3
	v_min_u32_e32 v147, 32, v147
	v_lshrrev_b32_e32 v176, 29, v4
	v_not_b32_e32 v171, v147
	v_alignbit_b32 v2, v3, v2, v171
	v_lshlrev_b32_e32 v3, 31, v176
	v_or_b32_e32 v171, 0x33000000, v3
	v_add_lshl_u32 v147, v147, v170, 23
	v_lshrrev_b32_e32 v2, 9, v2
	v_sub_u32_e32 v147, v171, v147
	v_or_b32_e32 v3, 0.5, v3
	v_lshlrev_b32_e32 v170, 23, v170
	v_or_b32_e32 v2, v147, v2
	v_lshrrev_b32_e32 v147, 9, v173
	v_sub_u32_e32 v3, v3, v170
	v_or_b32_e32 v3, v147, v3
	v_mul_f32_e32 v147, 0x3fc90fda, v3
	v_fma_f32 v170, v3, s55, -v147
	v_fmac_f32_e32 v170, 0x33a22168, v3
	v_fmac_f32_e32 v170, 0x3fc90fda, v2
	v_lshrrev_b32_e32 v2, 30, v4
	v_add_f32_e32 v3, v147, v170
	v_add_u32_e32 v2, v177, v2
